# GEMM K-loops: snake MFMA order (consecutive MFMAs share an operand) and no setprio 0/1 pair inside a segment
# speedup vs baseline: 1.0064x; 1.0064x over previous
.LBB0_249:
	s_lshl_b32 s2, s87, 7
	s_add_u32 s12, s84, s2
	s_addc_u32 s13, s85, 0
	s_add_u32 s4, s12, 0x100
	s_addc_u32 s5, s13, 0
	s_and_b64 s[2:3], s[92:93], exec
	v_add_u32_e32 v140, s0, v1
	s_mul_i32 s2, s87, 0x188800
	ds_read_b128 v[148:151], v140
	ds_read_b128 v[152:155], v140 offset:256
	ds_read_b128 v[156:159], v140 offset:8192
	ds_read_b128 v[160:163], v140 offset:8448
	v_add_u32_e32 v140, s1, v1
	s_cselect_b32 s5, s5, s81
	s_cselect_b32 s4, s4, s80
	s_add_u32 s2, s88, s2
	ds_read_b128 v[164:167], v140
	ds_read_b128 v[168:171], v140 offset:256
	ds_read_b128 v[172:175], v140 offset:8192
	ds_read_b128 v[176:179], v140 offset:8448
	s_addc_u32 s3, s89, 0
	s_add_u32 s20, s2, 0x311000
	s_addc_u32 s21, s3, 0
	s_and_b64 s[2:3], s[92:93], exec
	s_cselect_b32 s92, s20, s86
	s_cselect_b32 s93, s21, s75
	s_add_u32 s94, s92, 0x188800
	s_addc_u32 s95, s93, 0
	s_add_u32 s2, s12, 0x104080
	s_addc_u32 s3, s13, 0
	v_lshl_add_u64 v[140:141], s[2:3], 0, v[130:131]
	s_add_i32 m0, s68, 0xc000
	ds_read_b128 v[180:183], v145
	ds_read_b128 v[184:187], v145 offset:1024
	ds_read_b128 v[188:191], v145 offset:2048
	ds_read_b128 v[192:195], v145 offset:3072
	ds_read_b128 v[196:199], v145 offset:4096
	ds_read_b128 v[200:203], v145 offset:5120
	ds_read_b128 v[204:207], v145 offset:6144
	ds_read_b128 v[208:211], v145 offset:7168
	global_load_lds_dwordx4 v[140:141], off
	v_lshl_add_u64 v[140:141], s[2:3], 0, v[134:135]
	s_add_i32 m0, s68, 0xe000
	s_nop 0
	global_load_lds_dwordx4 v[140:141], off
	s_waitcnt vmcnt(8)
	s_waitcnt lgkmcnt(0)
	s_barrier
	s_setprio 1
	s_waitcnt lgkmcnt(0)
	v_mfma_f32_16x16x32_bf16 v[126:129], v[148:151], v[180:183], v[126:129]
	v_mfma_f32_16x16x32_bf16 v[122:125], v[152:155], v[180:183], v[122:125]
	v_mfma_f32_16x16x32_bf16 v[110:113], v[152:155], v[188:191], v[110:113]
	v_mfma_f32_16x16x32_bf16 v[118:121], v[148:151], v[188:191], v[118:121]
	v_mfma_f32_16x16x32_bf16 v[102:105], v[148:151], v[196:199], v[102:105]
	v_mfma_f32_16x16x32_bf16 v[94:97], v[152:155], v[196:199], v[94:97]
	v_mfma_f32_16x16x32_bf16 v[78:81], v[152:155], v[204:207], v[78:81]
	v_mfma_f32_16x16x32_bf16 v[86:89], v[148:151], v[204:207], v[86:89]
	v_mfma_f32_16x16x32_bf16 v[126:129], v[156:159], v[184:187], v[126:129]
	v_mfma_f32_16x16x32_bf16 v[122:125], v[160:163], v[184:187], v[122:125]
	v_mfma_f32_16x16x32_bf16 v[110:113], v[160:163], v[192:195], v[110:113]
	v_mfma_f32_16x16x32_bf16 v[118:121], v[156:159], v[192:195], v[118:121]
	v_mfma_f32_16x16x32_bf16 v[102:105], v[156:159], v[200:203], v[102:105]
	v_mfma_f32_16x16x32_bf16 v[94:97], v[160:163], v[200:203], v[94:97]
	v_mfma_f32_16x16x32_bf16 v[78:81], v[160:163], v[208:211], v[78:81]
	v_mfma_f32_16x16x32_bf16 v[86:89], v[156:159], v[208:211], v[86:89]
	v_mfma_f32_16x16x32_bf16 v[114:117], v[164:167], v[180:183], v[114:117]
	v_mfma_f32_16x16x32_bf16 v[106:109], v[168:171], v[180:183], v[106:109]
	v_mfma_f32_16x16x32_bf16 v[90:93], v[168:171], v[188:191], v[90:93]
	v_mfma_f32_16x16x32_bf16 v[98:101], v[164:167], v[188:191], v[98:101]
	v_mfma_f32_16x16x32_bf16 v[82:85], v[164:167], v[196:199], v[82:85]
	v_mfma_f32_16x16x32_bf16 v[74:77], v[168:171], v[196:199], v[74:77]
	v_mfma_f32_16x16x32_bf16 v[66:69], v[168:171], v[204:207], v[66:69]
	v_mfma_f32_16x16x32_bf16 v[70:73], v[164:167], v[204:207], v[70:73]
	v_mfma_f32_16x16x32_bf16 v[114:117], v[172:175], v[184:187], v[114:117]
	v_mfma_f32_16x16x32_bf16 v[106:109], v[176:179], v[184:187], v[106:109]
	v_mfma_f32_16x16x32_bf16 v[90:93], v[176:179], v[192:195], v[90:93]
	v_mfma_f32_16x16x32_bf16 v[98:101], v[172:175], v[192:195], v[98:101]
	v_mfma_f32_16x16x32_bf16 v[82:85], v[172:175], v[200:203], v[82:85]
	v_mfma_f32_16x16x32_bf16 v[74:77], v[176:179], v[200:203], v[74:77]
	v_mfma_f32_16x16x32_bf16 v[66:69], v[176:179], v[208:211], v[66:69]
	v_mfma_f32_16x16x32_bf16 v[70:73], v[172:175], v[208:211], v[70:73]
	s_setprio 0
	s_barrier
	s_add_i32 s2, s0, s15
	v_lshl_add_u64 v[140:141], s[92:93], 0, v[132:133]
	s_mov_b32 m0, s2
	ds_read_b128 v[180:183], v145 offset:16384
	ds_read_b128 v[184:187], v145 offset:17408
	ds_read_b128 v[188:191], v145 offset:18432
	ds_read_b128 v[192:195], v145 offset:19456
	ds_read_b128 v[196:199], v145 offset:20480
	ds_read_b128 v[200:203], v145 offset:21504
	ds_read_b128 v[204:207], v145 offset:22528
	ds_read_b128 v[208:211], v145 offset:23552
	global_load_lds_dwordx4 v[140:141], off
	v_lshl_add_u64 v[212:213], s[92:93], 0, v[136:137]
	s_add_i32 m0, s2, 0x2000
	s_add_i32 s2, s1, s15
	global_load_lds_dwordx4 v[212:213], off
	v_lshl_add_u64 v[140:141], v[140:141], 0, s[10:11]
	s_mov_b32 m0, s2
	s_nop 0
	global_load_lds_dwordx4 v[140:141], off
	v_lshl_add_u64 v[140:141], v[212:213], 0, s[10:11]
	s_add_i32 m0, s2, 0x2000
	v_lshl_add_u64 v[212:213], s[4:5], 0, v[134:135]
	global_load_lds_dwordx4 v[140:141], off
	v_lshl_add_u64 v[140:141], s[4:5], 0, v[130:131]
	s_mov_b32 m0, s68
	s_nop 0
	global_load_lds_dwordx4 v[140:141], off
	s_mov_b32 m0, s69
	s_nop 0
	global_load_lds_dwordx4 v[212:213], off
	s_waitcnt vmcnt(8)
	s_waitcnt lgkmcnt(0)
	s_barrier
	s_setprio 1
	s_waitcnt lgkmcnt(0)
	v_mfma_f32_16x16x32_bf16 v[62:65], v[148:151], v[180:183], v[62:65]
	v_mfma_f32_16x16x32_bf16 v[58:61], v[152:155], v[180:183], v[58:61]
	v_mfma_f32_16x16x32_bf16 v[46:49], v[152:155], v[188:191], v[46:49]
	v_mfma_f32_16x16x32_bf16 v[54:57], v[148:151], v[188:191], v[54:57]
	v_mfma_f32_16x16x32_bf16 v[38:41], v[148:151], v[196:199], v[38:41]
	v_mfma_f32_16x16x32_bf16 v[30:33], v[152:155], v[196:199], v[30:33]
	v_mfma_f32_16x16x32_bf16 v[14:17], v[152:155], v[204:207], v[14:17]
	v_mfma_f32_16x16x32_bf16 v[22:25], v[148:151], v[204:207], v[22:25]
	v_mfma_f32_16x16x32_bf16 v[62:65], v[156:159], v[184:187], v[62:65]
	v_mfma_f32_16x16x32_bf16 v[58:61], v[160:163], v[184:187], v[58:61]
	v_mfma_f32_16x16x32_bf16 v[46:49], v[160:163], v[192:195], v[46:49]
	v_mfma_f32_16x16x32_bf16 v[54:57], v[156:159], v[192:195], v[54:57]
	v_mfma_f32_16x16x32_bf16 v[38:41], v[156:159], v[200:203], v[38:41]
	v_mfma_f32_16x16x32_bf16 v[30:33], v[160:163], v[200:203], v[30:33]
	v_mfma_f32_16x16x32_bf16 v[14:17], v[160:163], v[208:211], v[14:17]
	v_mfma_f32_16x16x32_bf16 v[22:25], v[156:159], v[208:211], v[22:25]
	v_mfma_f32_16x16x32_bf16 v[50:53], v[164:167], v[180:183], v[50:53]
	v_mfma_f32_16x16x32_bf16 v[42:45], v[168:171], v[180:183], v[42:45]
	v_mfma_f32_16x16x32_bf16 v[26:29], v[168:171], v[188:191], v[26:29]
	v_mfma_f32_16x16x32_bf16 v[34:37], v[164:167], v[188:191], v[34:37]
	v_mfma_f32_16x16x32_bf16 v[18:21], v[164:167], v[196:199], v[18:21]
	v_mfma_f32_16x16x32_bf16 v[10:13], v[168:171], v[196:199], v[10:13]
	v_mfma_f32_16x16x32_bf16 v[2:5], v[168:171], v[204:207], v[2:5]
	v_mfma_f32_16x16x32_bf16 v[6:9], v[164:167], v[204:207], v[6:9]
	v_mfma_f32_16x16x32_bf16 v[50:53], v[172:175], v[184:187], v[50:53]
	v_mfma_f32_16x16x32_bf16 v[42:45], v[176:179], v[184:187], v[42:45]
	v_mfma_f32_16x16x32_bf16 v[26:29], v[176:179], v[192:195], v[26:29]
	v_mfma_f32_16x16x32_bf16 v[34:37], v[172:175], v[192:195], v[34:37]
	v_mfma_f32_16x16x32_bf16 v[18:21], v[172:175], v[200:203], v[18:21]
	v_mfma_f32_16x16x32_bf16 v[10:13], v[176:179], v[200:203], v[10:13]
	v_mfma_f32_16x16x32_bf16 v[2:5], v[176:179], v[208:211], v[2:5]
	v_mfma_f32_16x16x32_bf16 v[6:9], v[172:175], v[208:211], v[6:9]
	s_setprio 0
	s_barrier
	s_add_i32 s12, 0, 0x18000
	v_add_u32_e32 v147, s12, v1
	s_add_i32 s13, 0, 0x1c000
	ds_read_b128 v[148:151], v147
	ds_read_b128 v[152:155], v147 offset:256
	ds_read_b128 v[156:159], v147 offset:8192
	ds_read_b128 v[160:163], v147 offset:8448
	v_add_u32_e32 v147, s13, v1
	ds_read_b128 v[164:167], v147
	ds_read_b128 v[168:171], v147 offset:256
	ds_read_b128 v[172:175], v147 offset:8192
	ds_read_b128 v[176:179], v147 offset:8448
	s_add_u32 s2, s4, 0x104000
	s_addc_u32 s3, s5, 0
	s_mov_b32 m0, s70
	v_lshl_add_u64 v[214:215], s[2:3], 0, v[130:131]
	ds_read_b128 v[180:183], v145 offset:32768
	ds_read_b128 v[184:187], v145 offset:33792
	ds_read_b128 v[188:191], v145 offset:34816
	ds_read_b128 v[192:195], v145 offset:35840
	ds_read_b128 v[196:199], v145 offset:36864
	ds_read_b128 v[200:203], v145 offset:37888
	ds_read_b128 v[204:207], v145 offset:38912
	ds_read_b128 v[208:211], v145 offset:39936
	global_load_lds_dwordx4 v[214:215], off
	v_lshl_add_u64 v[214:215], s[2:3], 0, v[134:135]
	s_mov_b32 m0, s71
	s_nop 0
	global_load_lds_dwordx4 v[214:215], off
	s_waitcnt vmcnt(8)
	s_waitcnt lgkmcnt(0)
	s_barrier
	s_setprio 1
	s_waitcnt lgkmcnt(0)
	v_mfma_f32_16x16x32_bf16 v[126:129], v[148:151], v[180:183], v[126:129]
	v_mfma_f32_16x16x32_bf16 v[122:125], v[152:155], v[180:183], v[122:125]
	v_mfma_f32_16x16x32_bf16 v[110:113], v[152:155], v[188:191], v[110:113]
	v_mfma_f32_16x16x32_bf16 v[118:121], v[148:151], v[188:191], v[118:121]
	v_mfma_f32_16x16x32_bf16 v[102:105], v[148:151], v[196:199], v[102:105]
	v_mfma_f32_16x16x32_bf16 v[94:97], v[152:155], v[196:199], v[94:97]
	v_mfma_f32_16x16x32_bf16 v[78:81], v[152:155], v[204:207], v[78:81]
	v_mfma_f32_16x16x32_bf16 v[86:89], v[148:151], v[204:207], v[86:89]
	v_mfma_f32_16x16x32_bf16 v[126:129], v[156:159], v[184:187], v[126:129]
	v_mfma_f32_16x16x32_bf16 v[122:125], v[160:163], v[184:187], v[122:125]
	v_mfma_f32_16x16x32_bf16 v[110:113], v[160:163], v[192:195], v[110:113]
	v_mfma_f32_16x16x32_bf16 v[118:121], v[156:159], v[192:195], v[118:121]
	v_mfma_f32_16x16x32_bf16 v[102:105], v[156:159], v[200:203], v[102:105]
	v_mfma_f32_16x16x32_bf16 v[94:97], v[160:163], v[200:203], v[94:97]
	v_mfma_f32_16x16x32_bf16 v[78:81], v[160:163], v[208:211], v[78:81]
	v_mfma_f32_16x16x32_bf16 v[86:89], v[156:159], v[208:211], v[86:89]
	v_mfma_f32_16x16x32_bf16 v[114:117], v[164:167], v[180:183], v[114:117]
	v_mfma_f32_16x16x32_bf16 v[106:109], v[168:171], v[180:183], v[106:109]
	v_mfma_f32_16x16x32_bf16 v[90:93], v[168:171], v[188:191], v[90:93]
	v_mfma_f32_16x16x32_bf16 v[98:101], v[164:167], v[188:191], v[98:101]
	v_mfma_f32_16x16x32_bf16 v[82:85], v[164:167], v[196:199], v[82:85]
	v_mfma_f32_16x16x32_bf16 v[74:77], v[168:171], v[196:199], v[74:77]
	v_mfma_f32_16x16x32_bf16 v[66:69], v[168:171], v[204:207], v[66:69]
	v_mfma_f32_16x16x32_bf16 v[70:73], v[164:167], v[204:207], v[70:73]
	v_mfma_f32_16x16x32_bf16 v[114:117], v[172:175], v[184:187], v[114:117]
	v_mfma_f32_16x16x32_bf16 v[106:109], v[176:179], v[184:187], v[106:109]
	v_mfma_f32_16x16x32_bf16 v[90:93], v[176:179], v[192:195], v[90:93]
	v_mfma_f32_16x16x32_bf16 v[98:101], v[172:175], v[192:195], v[98:101]
	v_mfma_f32_16x16x32_bf16 v[82:85], v[172:175], v[200:203], v[82:85]
	v_mfma_f32_16x16x32_bf16 v[74:77], v[176:179], v[200:203], v[74:77]
	v_mfma_f32_16x16x32_bf16 v[66:69], v[176:179], v[208:211], v[66:69]
	v_mfma_f32_16x16x32_bf16 v[70:73], v[172:175], v[208:211], v[70:73]
	s_setprio 0
	s_barrier
	s_add_i32 s2, s12, s15
	v_lshl_add_u64 v[214:215], s[94:95], 0, v[132:133]
	s_mov_b32 m0, s2
	ds_read_b128 v[180:183], v145 offset:49152
	ds_read_b128 v[184:187], v145 offset:50176
	ds_read_b128 v[188:191], v145 offset:51200
	ds_read_b128 v[192:195], v145 offset:52224
	ds_read_b128 v[196:199], v145 offset:53248
	ds_read_b128 v[200:203], v145 offset:54272
	ds_read_b128 v[204:207], v145 offset:55296
	ds_read_b128 v[208:211], v145 offset:56320
	global_load_lds_dwordx4 v[214:215], off
	s_add_i32 m0, s2, 0x2000
	s_add_u32 s2, s92, 0x189000
	v_lshl_add_u64 v[214:215], s[94:95], 0, v[136:137]
	s_addc_u32 s3, s93, 0
	s_add_i32 s4, s13, s15
	global_load_lds_dwordx4 v[214:215], off
	v_lshl_add_u64 v[214:215], s[2:3], 0, v[132:133]
	s_mov_b32 m0, s4
	v_lshl_add_u64 v[140:141], v[140:141], 0, s[52:53]
	global_load_lds_dwordx4 v[214:215], off
	v_lshl_add_u64 v[214:215], s[2:3], 0, v[136:137]
	s_add_i32 m0, s4, 0x2000
	s_nop 0
	global_load_lds_dwordx4 v[214:215], off
	s_mov_b32 m0, s8
	s_nop 0
	global_load_lds_dwordx4 v[140:141], off
	v_lshl_add_u64 v[140:141], v[212:213], 0, s[52:53]
	s_mov_b32 m0, s9
	s_nop 0
	global_load_lds_dwordx4 v[140:141], off
	s_waitcnt vmcnt(8)
	s_waitcnt lgkmcnt(0)
	s_barrier
	s_setprio 1
	s_waitcnt lgkmcnt(0)
	v_mfma_f32_16x16x32_bf16 v[62:65], v[148:151], v[180:183], v[62:65]
	v_mfma_f32_16x16x32_bf16 v[58:61], v[152:155], v[180:183], v[58:61]
	v_mfma_f32_16x16x32_bf16 v[46:49], v[152:155], v[188:191], v[46:49]
	v_mfma_f32_16x16x32_bf16 v[54:57], v[148:151], v[188:191], v[54:57]
	v_mfma_f32_16x16x32_bf16 v[38:41], v[148:151], v[196:199], v[38:41]
	v_mfma_f32_16x16x32_bf16 v[30:33], v[152:155], v[196:199], v[30:33]
	v_mfma_f32_16x16x32_bf16 v[14:17], v[152:155], v[204:207], v[14:17]
	v_mfma_f32_16x16x32_bf16 v[22:25], v[148:151], v[204:207], v[22:25]
	v_mfma_f32_16x16x32_bf16 v[62:65], v[156:159], v[184:187], v[62:65]
	v_mfma_f32_16x16x32_bf16 v[58:61], v[160:163], v[184:187], v[58:61]
	v_mfma_f32_16x16x32_bf16 v[46:49], v[160:163], v[192:195], v[46:49]
	v_mfma_f32_16x16x32_bf16 v[54:57], v[156:159], v[192:195], v[54:57]
	v_mfma_f32_16x16x32_bf16 v[38:41], v[156:159], v[200:203], v[38:41]
	v_mfma_f32_16x16x32_bf16 v[30:33], v[160:163], v[200:203], v[30:33]
	v_mfma_f32_16x16x32_bf16 v[14:17], v[160:163], v[208:211], v[14:17]
	v_mfma_f32_16x16x32_bf16 v[22:25], v[156:159], v[208:211], v[22:25]
	v_mfma_f32_16x16x32_bf16 v[50:53], v[164:167], v[180:183], v[50:53]
	v_mfma_f32_16x16x32_bf16 v[42:45], v[168:171], v[180:183], v[42:45]
	v_mfma_f32_16x16x32_bf16 v[26:29], v[168:171], v[188:191], v[26:29]
	v_mfma_f32_16x16x32_bf16 v[34:37], v[164:167], v[188:191], v[34:37]
	v_mfma_f32_16x16x32_bf16 v[18:21], v[164:167], v[196:199], v[18:21]
	v_mfma_f32_16x16x32_bf16 v[10:13], v[168:171], v[196:199], v[10:13]
	v_mfma_f32_16x16x32_bf16 v[2:5], v[168:171], v[204:207], v[2:5]
	v_mfma_f32_16x16x32_bf16 v[6:9], v[164:167], v[204:207], v[6:9]
	v_mfma_f32_16x16x32_bf16 v[50:53], v[172:175], v[184:187], v[50:53]
	v_mfma_f32_16x16x32_bf16 v[42:45], v[176:179], v[184:187], v[42:45]
	v_mfma_f32_16x16x32_bf16 v[26:29], v[176:179], v[192:195], v[26:29]
	v_mfma_f32_16x16x32_bf16 v[34:37], v[172:175], v[192:195], v[34:37]
	v_mfma_f32_16x16x32_bf16 v[18:21], v[172:175], v[200:203], v[18:21]
	v_mfma_f32_16x16x32_bf16 v[10:13], v[176:179], v[200:203], v[10:13]
	v_mfma_f32_16x16x32_bf16 v[2:5], v[176:179], v[208:211], v[2:5]
	v_mfma_f32_16x16x32_bf16 v[6:9], v[172:175], v[208:211], v[6:9]
	s_setprio 0
	s_barrier
	s_add_i32 s2, s87, 2
	s_cmp_gt_u32 s87, 61
	s_cbranch_scc1 .LBB0_255
	s_mov_b32 s87, s2
	s_branch .LBB0_220

.LBB0_558:
	s_lshl_b32 s2, s69, 7
	s_add_u32 s20, s74, s2
	s_addc_u32 s21, s75, 0
	s_add_u32 s4, s20, 0x100
	s_addc_u32 s5, s21, 0
	s_and_b64 s[2:3], s[82:83], exec
	s_mul_i32 s2, s69, 0x88800
	v_add_u32_e32 v188, s93, v1
	v_add_u32_e32 v204, s18, v1
	s_cselect_b32 s5, s5, s63
	s_cselect_b32 s4, s4, s62
	s_add_u32 s2, s78, s2
	ds_read_b128 v[130:133], v188
	ds_read_b128 v[134:137], v188 offset:256
	ds_read_b128 v[180:183], v188 offset:8192
	ds_read_b128 v[188:191], v188 offset:8448
	ds_read_b128 v[192:195], v204
	ds_read_b128 v[196:199], v204 offset:256
	ds_read_b128 v[200:203], v204 offset:8192
	ds_read_b128 v[204:207], v204 offset:8448
	s_addc_u32 s3, s79, 0
	s_add_u32 s22, s2, 0x111000
	s_addc_u32 s23, s3, 0
	s_and_b64 s[2:3], s[82:83], exec
	s_cselect_b32 s82, s22, s61
	s_cselect_b32 s83, s23, s14
	s_add_u32 s84, s82, 0x88800
	s_addc_u32 s85, s83, 0
	s_add_u32 s2, s20, 0x104080
	s_addc_u32 s3, s21, 0
	v_lshl_add_u64 v[240:241], s[2:3], 0, v[138:139]
	s_add_i32 m0, s94, 0xc000
	ds_read_b128 v[208:211], v186
	ds_read_b128 v[212:215], v186 offset:1024
	ds_read_b128 v[216:219], v186 offset:2048
	ds_read_b128 v[220:223], v186 offset:3072
	ds_read_b128 v[224:227], v186 offset:4096
	ds_read_b128 v[228:231], v186 offset:5120
	ds_read_b128 v[232:235], v186 offset:6144
	ds_read_b128 v[236:239], v186 offset:7168
	global_load_lds_dwordx4 v[240:241], off
	v_lshl_add_u64 v[240:241], s[2:3], 0, v[142:143]
	s_add_i32 m0, s94, 0xe000
	s_nop 0
	global_load_lds_dwordx4 v[240:241], off
	s_waitcnt vmcnt(8)
	s_waitcnt lgkmcnt(0)
	s_barrier
	s_setprio 1
	s_waitcnt lgkmcnt(0)
	v_mfma_f32_16x16x32_bf16 v[126:129], v[130:133], v[208:211], v[126:129]
	v_mfma_f32_16x16x32_bf16 v[122:125], v[134:137], v[208:211], v[122:125]
	v_mfma_f32_16x16x32_bf16 v[106:109], v[134:137], v[216:219], v[106:109]
	v_mfma_f32_16x16x32_bf16 v[110:113], v[130:133], v[216:219], v[110:113]
	v_mfma_f32_16x16x32_bf16 v[94:97], v[130:133], v[224:227], v[94:97]
	v_mfma_f32_16x16x32_bf16 v[90:93], v[134:137], v[224:227], v[90:93]
	v_mfma_f32_16x16x32_bf16 v[74:77], v[134:137], v[232:235], v[74:77]
	v_mfma_f32_16x16x32_bf16 v[78:81], v[130:133], v[232:235], v[78:81]
	v_mfma_f32_16x16x32_bf16 v[126:129], v[180:183], v[212:215], v[126:129]
	v_mfma_f32_16x16x32_bf16 v[122:125], v[188:191], v[212:215], v[122:125]
	v_mfma_f32_16x16x32_bf16 v[106:109], v[188:191], v[220:223], v[106:109]
	v_mfma_f32_16x16x32_bf16 v[110:113], v[180:183], v[220:223], v[110:113]
	v_mfma_f32_16x16x32_bf16 v[94:97], v[180:183], v[228:231], v[94:97]
	v_mfma_f32_16x16x32_bf16 v[90:93], v[188:191], v[228:231], v[90:93]
	v_mfma_f32_16x16x32_bf16 v[74:77], v[188:191], v[236:239], v[74:77]
	v_mfma_f32_16x16x32_bf16 v[78:81], v[180:183], v[236:239], v[78:81]
	v_mfma_f32_16x16x32_bf16 v[118:121], v[192:195], v[208:211], v[118:121]
	v_mfma_f32_16x16x32_bf16 v[114:117], v[196:199], v[208:211], v[114:117]
	v_mfma_f32_16x16x32_bf16 v[98:101], v[196:199], v[216:219], v[98:101]
	v_mfma_f32_16x16x32_bf16 v[102:105], v[192:195], v[216:219], v[102:105]
	v_mfma_f32_16x16x32_bf16 v[86:89], v[192:195], v[224:227], v[86:89]
	v_mfma_f32_16x16x32_bf16 v[82:85], v[196:199], v[224:227], v[82:85]
	v_mfma_f32_16x16x32_bf16 v[66:69], v[196:199], v[232:235], v[66:69]
	v_mfma_f32_16x16x32_bf16 v[70:73], v[192:195], v[232:235], v[70:73]
	v_mfma_f32_16x16x32_bf16 v[118:121], v[200:203], v[212:215], v[118:121]
	v_mfma_f32_16x16x32_bf16 v[114:117], v[204:207], v[212:215], v[114:117]
	v_mfma_f32_16x16x32_bf16 v[98:101], v[204:207], v[220:223], v[98:101]
	v_mfma_f32_16x16x32_bf16 v[102:105], v[200:203], v[220:223], v[102:105]
	v_mfma_f32_16x16x32_bf16 v[86:89], v[200:203], v[228:231], v[86:89]
	v_mfma_f32_16x16x32_bf16 v[82:85], v[204:207], v[228:231], v[82:85]
	v_mfma_f32_16x16x32_bf16 v[66:69], v[204:207], v[236:239], v[66:69]
	v_mfma_f32_16x16x32_bf16 v[70:73], v[200:203], v[236:239], v[70:73]
	s_setprio 0
	s_barrier
	s_add_i32 s2, s93, s73
	v_lshl_add_u64 v[240:241], s[82:83], 0, v[140:141]
	s_mov_b32 m0, s2
	ds_read_b128 v[208:211], v186 offset:16384
	ds_read_b128 v[212:215], v186 offset:17408
	ds_read_b128 v[216:219], v186 offset:18432
	ds_read_b128 v[220:223], v186 offset:19456
	ds_read_b128 v[224:227], v186 offset:20480
	ds_read_b128 v[228:231], v186 offset:21504
	ds_read_b128 v[232:235], v186 offset:22528
	ds_read_b128 v[236:239], v186 offset:23552
	global_load_lds_dwordx4 v[240:241], off
	v_lshl_add_u64 v[242:243], s[82:83], 0, v[144:145]
	s_add_i32 m0, s2, 0x2000
	s_add_i32 s2, s18, s73
	global_load_lds_dwordx4 v[242:243], off
	v_lshl_add_u64 v[240:241], v[240:241], 0, s[12:13]
	s_mov_b32 m0, s2
	s_nop 0
	global_load_lds_dwordx4 v[240:241], off
	v_lshl_add_u64 v[240:241], v[242:243], 0, s[12:13]
	s_add_i32 m0, s2, 0x2000
	v_lshl_add_u64 v[242:243], s[4:5], 0, v[142:143]
	global_load_lds_dwordx4 v[240:241], off
	v_lshl_add_u64 v[240:241], s[4:5], 0, v[138:139]
	s_mov_b32 m0, s94
	s_nop 0
	global_load_lds_dwordx4 v[240:241], off
	s_mov_b32 m0, s95
	s_nop 0
	global_load_lds_dwordx4 v[242:243], off
	s_waitcnt vmcnt(8)
	s_waitcnt lgkmcnt(0)
	s_barrier
	s_setprio 1
	s_waitcnt lgkmcnt(0)
	v_mfma_f32_16x16x32_bf16 v[62:65], v[130:133], v[208:211], v[62:65]
	v_mfma_f32_16x16x32_bf16 v[58:61], v[134:137], v[208:211], v[58:61]
	v_mfma_f32_16x16x32_bf16 v[42:45], v[134:137], v[216:219], v[42:45]
	v_mfma_f32_16x16x32_bf16 v[46:49], v[130:133], v[216:219], v[46:49]
	v_mfma_f32_16x16x32_bf16 v[30:33], v[130:133], v[224:227], v[30:33]
	v_mfma_f32_16x16x32_bf16 v[26:29], v[134:137], v[224:227], v[26:29]
	v_mfma_f32_16x16x32_bf16 v[10:13], v[134:137], v[232:235], v[10:13]
	v_mfma_f32_16x16x32_bf16 v[14:17], v[130:133], v[232:235], v[14:17]
	v_mfma_f32_16x16x32_bf16 v[62:65], v[180:183], v[212:215], v[62:65]
	v_mfma_f32_16x16x32_bf16 v[58:61], v[188:191], v[212:215], v[58:61]
	v_mfma_f32_16x16x32_bf16 v[42:45], v[188:191], v[220:223], v[42:45]
	v_mfma_f32_16x16x32_bf16 v[46:49], v[180:183], v[220:223], v[46:49]
	v_mfma_f32_16x16x32_bf16 v[30:33], v[180:183], v[228:231], v[30:33]
	v_mfma_f32_16x16x32_bf16 v[26:29], v[188:191], v[228:231], v[26:29]
	v_mfma_f32_16x16x32_bf16 v[10:13], v[188:191], v[236:239], v[10:13]
	v_mfma_f32_16x16x32_bf16 v[14:17], v[180:183], v[236:239], v[14:17]
	v_mfma_f32_16x16x32_bf16 v[54:57], v[192:195], v[208:211], v[54:57]
	v_mfma_f32_16x16x32_bf16 v[50:53], v[196:199], v[208:211], v[50:53]
	v_mfma_f32_16x16x32_bf16 v[34:37], v[196:199], v[216:219], v[34:37]
	v_mfma_f32_16x16x32_bf16 v[38:41], v[192:195], v[216:219], v[38:41]
	v_mfma_f32_16x16x32_bf16 v[22:25], v[192:195], v[224:227], v[22:25]
	v_mfma_f32_16x16x32_bf16 v[18:21], v[196:199], v[224:227], v[18:21]
	v_mfma_f32_16x16x32_bf16 v[2:5], v[196:199], v[232:235], v[2:5]
	v_mfma_f32_16x16x32_bf16 v[6:9], v[192:195], v[232:235], v[6:9]
	v_mfma_f32_16x16x32_bf16 v[54:57], v[200:203], v[212:215], v[54:57]
	v_mfma_f32_16x16x32_bf16 v[50:53], v[204:207], v[212:215], v[50:53]
	v_mfma_f32_16x16x32_bf16 v[34:37], v[204:207], v[220:223], v[34:37]
	v_mfma_f32_16x16x32_bf16 v[38:41], v[200:203], v[220:223], v[38:41]
	v_mfma_f32_16x16x32_bf16 v[22:25], v[200:203], v[228:231], v[22:25]
	v_mfma_f32_16x16x32_bf16 v[18:21], v[204:207], v[228:231], v[18:21]
	v_mfma_f32_16x16x32_bf16 v[2:5], v[204:207], v[236:239], v[2:5]
	v_mfma_f32_16x16x32_bf16 v[6:9], v[200:203], v[236:239], v[6:9]
	s_setprio 0
	s_barrier
	s_add_i32 s20, 0, 0x18000
	s_add_i32 s21, 0, 0x1c000
	v_add_u32_e32 v188, s20, v1
	v_add_u32_e32 v204, s21, v1
	ds_read_b128 v[130:133], v188
	ds_read_b128 v[134:137], v188 offset:256
	ds_read_b128 v[180:183], v188 offset:8192
	ds_read_b128 v[188:191], v188 offset:8448
	ds_read_b128 v[192:195], v204
	ds_read_b128 v[196:199], v204 offset:256
	ds_read_b128 v[200:203], v204 offset:8192
	ds_read_b128 v[204:207], v204 offset:8448
	s_add_u32 s2, s4, 0x104000
	s_addc_u32 s3, s5, 0
	s_mov_b32 m0, s96
	v_lshl_add_u64 v[244:245], s[2:3], 0, v[138:139]
	ds_read_b128 v[208:211], v186 offset:32768
	ds_read_b128 v[212:215], v186 offset:33792
	ds_read_b128 v[216:219], v186 offset:34816
	ds_read_b128 v[220:223], v186 offset:35840
	ds_read_b128 v[224:227], v186 offset:36864
	ds_read_b128 v[228:231], v186 offset:37888
	ds_read_b128 v[232:235], v186 offset:38912
	ds_read_b128 v[236:239], v186 offset:39936
	global_load_lds_dwordx4 v[244:245], off
	v_lshl_add_u64 v[244:245], s[2:3], 0, v[142:143]
	s_mov_b32 m0, s97
	s_nop 0
	global_load_lds_dwordx4 v[244:245], off
	s_waitcnt vmcnt(8)
	s_waitcnt lgkmcnt(0)
	s_barrier
	s_setprio 1
	s_waitcnt lgkmcnt(0)
	v_mfma_f32_16x16x32_bf16 v[126:129], v[130:133], v[208:211], v[126:129]
	v_mfma_f32_16x16x32_bf16 v[122:125], v[134:137], v[208:211], v[122:125]
	v_mfma_f32_16x16x32_bf16 v[106:109], v[134:137], v[216:219], v[106:109]
	v_mfma_f32_16x16x32_bf16 v[110:113], v[130:133], v[216:219], v[110:113]
	v_mfma_f32_16x16x32_bf16 v[94:97], v[130:133], v[224:227], v[94:97]
	v_mfma_f32_16x16x32_bf16 v[90:93], v[134:137], v[224:227], v[90:93]
	v_mfma_f32_16x16x32_bf16 v[74:77], v[134:137], v[232:235], v[74:77]
	v_mfma_f32_16x16x32_bf16 v[78:81], v[130:133], v[232:235], v[78:81]
	v_mfma_f32_16x16x32_bf16 v[126:129], v[180:183], v[212:215], v[126:129]
	v_mfma_f32_16x16x32_bf16 v[122:125], v[188:191], v[212:215], v[122:125]
	v_mfma_f32_16x16x32_bf16 v[106:109], v[188:191], v[220:223], v[106:109]
	v_mfma_f32_16x16x32_bf16 v[110:113], v[180:183], v[220:223], v[110:113]
	v_mfma_f32_16x16x32_bf16 v[94:97], v[180:183], v[228:231], v[94:97]
	v_mfma_f32_16x16x32_bf16 v[90:93], v[188:191], v[228:231], v[90:93]
	v_mfma_f32_16x16x32_bf16 v[74:77], v[188:191], v[236:239], v[74:77]
	v_mfma_f32_16x16x32_bf16 v[78:81], v[180:183], v[236:239], v[78:81]
	v_mfma_f32_16x16x32_bf16 v[118:121], v[192:195], v[208:211], v[118:121]
	v_mfma_f32_16x16x32_bf16 v[114:117], v[196:199], v[208:211], v[114:117]
	v_mfma_f32_16x16x32_bf16 v[98:101], v[196:199], v[216:219], v[98:101]
	v_mfma_f32_16x16x32_bf16 v[102:105], v[192:195], v[216:219], v[102:105]
	v_mfma_f32_16x16x32_bf16 v[86:89], v[192:195], v[224:227], v[86:89]
	v_mfma_f32_16x16x32_bf16 v[82:85], v[196:199], v[224:227], v[82:85]
	v_mfma_f32_16x16x32_bf16 v[66:69], v[196:199], v[232:235], v[66:69]
	v_mfma_f32_16x16x32_bf16 v[70:73], v[192:195], v[232:235], v[70:73]
	v_mfma_f32_16x16x32_bf16 v[118:121], v[200:203], v[212:215], v[118:121]
	v_mfma_f32_16x16x32_bf16 v[114:117], v[204:207], v[212:215], v[114:117]
	v_mfma_f32_16x16x32_bf16 v[98:101], v[204:207], v[220:223], v[98:101]
	v_mfma_f32_16x16x32_bf16 v[102:105], v[200:203], v[220:223], v[102:105]
	v_mfma_f32_16x16x32_bf16 v[86:89], v[200:203], v[228:231], v[86:89]
	v_mfma_f32_16x16x32_bf16 v[82:85], v[204:207], v[228:231], v[82:85]
	v_mfma_f32_16x16x32_bf16 v[66:69], v[204:207], v[236:239], v[66:69]
	v_mfma_f32_16x16x32_bf16 v[70:73], v[200:203], v[236:239], v[70:73]
	s_setprio 0
	s_barrier
	s_add_i32 s2, s20, s73
	v_lshl_add_u64 v[244:245], s[84:85], 0, v[140:141]
	s_mov_b32 m0, s2
	ds_read_b128 v[208:211], v186 offset:49152
	ds_read_b128 v[212:215], v186 offset:50176
	ds_read_b128 v[216:219], v186 offset:51200
	ds_read_b128 v[220:223], v186 offset:52224
	ds_read_b128 v[224:227], v186 offset:53248
	ds_read_b128 v[228:231], v186 offset:54272
	ds_read_b128 v[232:235], v186 offset:55296
	ds_read_b128 v[236:239], v186 offset:56320
	global_load_lds_dwordx4 v[244:245], off
	s_add_i32 m0, s2, 0x2000
	s_add_u32 s2, s82, 0x89000
	v_lshl_add_u64 v[244:245], s[84:85], 0, v[144:145]
	s_addc_u32 s3, s83, 0
	s_add_i32 s4, s21, s73
	global_load_lds_dwordx4 v[244:245], off
	v_lshl_add_u64 v[244:245], s[2:3], 0, v[140:141]
	s_mov_b32 m0, s4
	v_lshl_add_u64 v[240:241], v[240:241], 0, s[56:57]
	global_load_lds_dwordx4 v[244:245], off
	v_lshl_add_u64 v[244:245], s[2:3], 0, v[144:145]
	s_add_i32 m0, s4, 0x2000
	s_nop 0
	global_load_lds_dwordx4 v[244:245], off
	s_mov_b32 m0, s53
	s_nop 0
	global_load_lds_dwordx4 v[240:241], off
	v_lshl_add_u64 v[240:241], v[242:243], 0, s[56:57]
	s_mov_b32 m0, s92
	s_nop 0
	global_load_lds_dwordx4 v[240:241], off
	s_waitcnt vmcnt(8)
	s_waitcnt lgkmcnt(0)
	s_barrier
	s_setprio 1
	s_waitcnt lgkmcnt(0)
	v_mfma_f32_16x16x32_bf16 v[62:65], v[130:133], v[208:211], v[62:65]
	v_mfma_f32_16x16x32_bf16 v[58:61], v[134:137], v[208:211], v[58:61]
	v_mfma_f32_16x16x32_bf16 v[42:45], v[134:137], v[216:219], v[42:45]
	v_mfma_f32_16x16x32_bf16 v[46:49], v[130:133], v[216:219], v[46:49]
	v_mfma_f32_16x16x32_bf16 v[30:33], v[130:133], v[224:227], v[30:33]
	v_mfma_f32_16x16x32_bf16 v[26:29], v[134:137], v[224:227], v[26:29]
	v_mfma_f32_16x16x32_bf16 v[10:13], v[134:137], v[232:235], v[10:13]
	v_mfma_f32_16x16x32_bf16 v[14:17], v[130:133], v[232:235], v[14:17]
	v_mfma_f32_16x16x32_bf16 v[62:65], v[180:183], v[212:215], v[62:65]
	v_mfma_f32_16x16x32_bf16 v[58:61], v[188:191], v[212:215], v[58:61]
	v_mfma_f32_16x16x32_bf16 v[42:45], v[188:191], v[220:223], v[42:45]
	v_mfma_f32_16x16x32_bf16 v[46:49], v[180:183], v[220:223], v[46:49]
	v_mfma_f32_16x16x32_bf16 v[30:33], v[180:183], v[228:231], v[30:33]
	v_mfma_f32_16x16x32_bf16 v[26:29], v[188:191], v[228:231], v[26:29]
	v_mfma_f32_16x16x32_bf16 v[10:13], v[188:191], v[236:239], v[10:13]
	v_mfma_f32_16x16x32_bf16 v[14:17], v[180:183], v[236:239], v[14:17]
	v_mfma_f32_16x16x32_bf16 v[54:57], v[192:195], v[208:211], v[54:57]
	v_mfma_f32_16x16x32_bf16 v[50:53], v[196:199], v[208:211], v[50:53]
	v_mfma_f32_16x16x32_bf16 v[34:37], v[196:199], v[216:219], v[34:37]
	v_mfma_f32_16x16x32_bf16 v[38:41], v[192:195], v[216:219], v[38:41]
	v_mfma_f32_16x16x32_bf16 v[22:25], v[192:195], v[224:227], v[22:25]
	v_mfma_f32_16x16x32_bf16 v[18:21], v[196:199], v[224:227], v[18:21]
	v_mfma_f32_16x16x32_bf16 v[2:5], v[196:199], v[232:235], v[2:5]
	v_mfma_f32_16x16x32_bf16 v[6:9], v[192:195], v[232:235], v[6:9]
	v_mfma_f32_16x16x32_bf16 v[54:57], v[200:203], v[212:215], v[54:57]
	v_mfma_f32_16x16x32_bf16 v[50:53], v[204:207], v[212:215], v[50:53]
	v_mfma_f32_16x16x32_bf16 v[34:37], v[204:207], v[220:223], v[34:37]
	v_mfma_f32_16x16x32_bf16 v[38:41], v[200:203], v[220:223], v[38:41]
	v_mfma_f32_16x16x32_bf16 v[22:25], v[200:203], v[228:231], v[22:25]
	v_mfma_f32_16x16x32_bf16 v[18:21], v[204:207], v[228:231], v[18:21]
	v_mfma_f32_16x16x32_bf16 v[2:5], v[204:207], v[236:239], v[2:5]
	v_mfma_f32_16x16x32_bf16 v[6:9], v[200:203], v[236:239], v[6:9]
	s_setprio 0
	s_barrier
	s_add_i32 s2, s69, 2
	s_cmp_gt_u32 s69, 61
	s_cbranch_scc1 .LBB0_564
	s_mov_b32 s69, s2
	s_branch .LBB0_529

.LBB0_796:
	s_lshl_b32 s2, s90, 7
	s_add_u32 s20, s54, s2
	s_addc_u32 s21, s55, 0
	s_add_u32 s4, s20, 0x100
	s_addc_u32 s5, s21, 0
	s_and_b64 s[2:3], s[60:61], exec
	v_add_u32_e32 v140, s83, v1
	s_mul_i32 s2, s90, 0x208800
	ds_read_b128 v[148:151], v140
	ds_read_b128 v[152:155], v140 offset:256
	ds_read_b128 v[156:159], v140 offset:8192
	ds_read_b128 v[160:163], v140 offset:8448
	v_add_u32_e32 v140, s84, v1
	s_cselect_b32 s5, s5, s43
	s_cselect_b32 s4, s4, s42
	s_add_u32 s2, s56, s2
	ds_read_b128 v[164:167], v140
	ds_read_b128 v[168:171], v140 offset:256
	ds_read_b128 v[172:175], v140 offset:8192
	ds_read_b128 v[176:179], v140 offset:8448
	s_addc_u32 s3, s57, 0
	s_add_u32 s22, s2, 0x411000
	s_addc_u32 s23, s3, 0
	s_and_b64 s[2:3], s[60:61], exec
	s_cselect_b32 s60, s22, s89
	s_cselect_b32 s61, s23, s35
	s_add_u32 s62, s60, 0x208800
	s_addc_u32 s63, s61, 0
	s_add_u32 s2, s20, 0x104080
	s_addc_u32 s3, s21, 0
	v_lshl_add_u64 v[140:141], s[2:3], 0, v[130:131]
	s_add_i32 m0, s36, 0xc000
	ds_read_b128 v[180:183], v145
	ds_read_b128 v[184:187], v145 offset:1024
	ds_read_b128 v[188:191], v145 offset:2048
	ds_read_b128 v[192:195], v145 offset:3072
	ds_read_b128 v[196:199], v145 offset:4096
	ds_read_b128 v[200:203], v145 offset:5120
	ds_read_b128 v[204:207], v145 offset:6144
	ds_read_b128 v[208:211], v145 offset:7168
	global_load_lds_dwordx4 v[140:141], off
	v_lshl_add_u64 v[140:141], s[2:3], 0, v[134:135]
	s_add_i32 m0, s36, 0xe000
	s_nop 0
	global_load_lds_dwordx4 v[140:141], off
	s_waitcnt vmcnt(8)
	s_waitcnt lgkmcnt(0)
	s_barrier
	s_setprio 1
	s_waitcnt lgkmcnt(0)
	v_mfma_f32_16x16x32_bf16 v[126:129], v[148:151], v[180:183], v[126:129]
	v_mfma_f32_16x16x32_bf16 v[122:125], v[152:155], v[180:183], v[122:125]
	v_mfma_f32_16x16x32_bf16 v[106:109], v[152:155], v[188:191], v[106:109]
	v_mfma_f32_16x16x32_bf16 v[110:113], v[148:151], v[188:191], v[110:113]
	v_mfma_f32_16x16x32_bf16 v[94:97], v[148:151], v[196:199], v[94:97]
	v_mfma_f32_16x16x32_bf16 v[90:93], v[152:155], v[196:199], v[90:93]
	v_mfma_f32_16x16x32_bf16 v[74:77], v[152:155], v[204:207], v[74:77]
	v_mfma_f32_16x16x32_bf16 v[78:81], v[148:151], v[204:207], v[78:81]
	v_mfma_f32_16x16x32_bf16 v[126:129], v[156:159], v[184:187], v[126:129]
	v_mfma_f32_16x16x32_bf16 v[122:125], v[160:163], v[184:187], v[122:125]
	v_mfma_f32_16x16x32_bf16 v[106:109], v[160:163], v[192:195], v[106:109]
	v_mfma_f32_16x16x32_bf16 v[110:113], v[156:159], v[192:195], v[110:113]
	v_mfma_f32_16x16x32_bf16 v[94:97], v[156:159], v[200:203], v[94:97]
	v_mfma_f32_16x16x32_bf16 v[90:93], v[160:163], v[200:203], v[90:93]
	v_mfma_f32_16x16x32_bf16 v[74:77], v[160:163], v[208:211], v[74:77]
	v_mfma_f32_16x16x32_bf16 v[78:81], v[156:159], v[208:211], v[78:81]
	v_mfma_f32_16x16x32_bf16 v[118:121], v[164:167], v[180:183], v[118:121]
	v_mfma_f32_16x16x32_bf16 v[114:117], v[168:171], v[180:183], v[114:117]
	v_mfma_f32_16x16x32_bf16 v[98:101], v[168:171], v[188:191], v[98:101]
	v_mfma_f32_16x16x32_bf16 v[102:105], v[164:167], v[188:191], v[102:105]
	v_mfma_f32_16x16x32_bf16 v[86:89], v[164:167], v[196:199], v[86:89]
	v_mfma_f32_16x16x32_bf16 v[82:85], v[168:171], v[196:199], v[82:85]
	v_mfma_f32_16x16x32_bf16 v[66:69], v[168:171], v[204:207], v[66:69]
	v_mfma_f32_16x16x32_bf16 v[70:73], v[164:167], v[204:207], v[70:73]
	v_mfma_f32_16x16x32_bf16 v[118:121], v[172:175], v[184:187], v[118:121]
	v_mfma_f32_16x16x32_bf16 v[114:117], v[176:179], v[184:187], v[114:117]
	v_mfma_f32_16x16x32_bf16 v[98:101], v[176:179], v[192:195], v[98:101]
	v_mfma_f32_16x16x32_bf16 v[102:105], v[172:175], v[192:195], v[102:105]
	v_mfma_f32_16x16x32_bf16 v[86:89], v[172:175], v[200:203], v[86:89]
	v_mfma_f32_16x16x32_bf16 v[82:85], v[176:179], v[200:203], v[82:85]
	v_mfma_f32_16x16x32_bf16 v[66:69], v[176:179], v[208:211], v[66:69]
	v_mfma_f32_16x16x32_bf16 v[70:73], v[172:175], v[208:211], v[70:73]
	s_setprio 0
	s_barrier
	s_add_i32 s2, s83, s18
	v_lshl_add_u64 v[140:141], s[60:61], 0, v[132:133]
	s_mov_b32 m0, s2
	ds_read_b128 v[180:183], v145 offset:16384
	ds_read_b128 v[184:187], v145 offset:17408
	ds_read_b128 v[188:191], v145 offset:18432
	ds_read_b128 v[192:195], v145 offset:19456
	ds_read_b128 v[196:199], v145 offset:20480
	ds_read_b128 v[200:203], v145 offset:21504
	ds_read_b128 v[204:207], v145 offset:22528
	ds_read_b128 v[208:211], v145 offset:23552
	global_load_lds_dwordx4 v[140:141], off
	v_lshl_add_u64 v[212:213], s[60:61], 0, v[136:137]
	s_add_i32 m0, s2, 0x2000
	s_add_i32 s2, s84, s18
	global_load_lds_dwordx4 v[212:213], off
	v_lshl_add_u64 v[140:141], v[140:141], 0, s[10:11]
	s_mov_b32 m0, s2
	s_nop 0
	global_load_lds_dwordx4 v[140:141], off
	v_lshl_add_u64 v[140:141], v[212:213], 0, s[10:11]
	s_add_i32 m0, s2, 0x2000
	v_lshl_add_u64 v[212:213], s[4:5], 0, v[134:135]
	global_load_lds_dwordx4 v[140:141], off
	v_lshl_add_u64 v[140:141], s[4:5], 0, v[130:131]
	s_mov_b32 m0, s36
	s_nop 0
	global_load_lds_dwordx4 v[140:141], off
	s_mov_b32 m0, s37
	s_nop 0
	global_load_lds_dwordx4 v[212:213], off
	s_waitcnt vmcnt(8)
	s_waitcnt lgkmcnt(0)
	s_barrier
	s_setprio 1
	s_waitcnt lgkmcnt(0)
	v_mfma_f32_16x16x32_bf16 v[62:65], v[148:151], v[180:183], v[62:65]
	v_mfma_f32_16x16x32_bf16 v[58:61], v[152:155], v[180:183], v[58:61]
	v_mfma_f32_16x16x32_bf16 v[42:45], v[152:155], v[188:191], v[42:45]
	v_mfma_f32_16x16x32_bf16 v[46:49], v[148:151], v[188:191], v[46:49]
	v_mfma_f32_16x16x32_bf16 v[30:33], v[148:151], v[196:199], v[30:33]
	v_mfma_f32_16x16x32_bf16 v[26:29], v[152:155], v[196:199], v[26:29]
	v_mfma_f32_16x16x32_bf16 v[10:13], v[152:155], v[204:207], v[10:13]
	v_mfma_f32_16x16x32_bf16 v[14:17], v[148:151], v[204:207], v[14:17]
	v_mfma_f32_16x16x32_bf16 v[62:65], v[156:159], v[184:187], v[62:65]
	v_mfma_f32_16x16x32_bf16 v[58:61], v[160:163], v[184:187], v[58:61]
	v_mfma_f32_16x16x32_bf16 v[42:45], v[160:163], v[192:195], v[42:45]
	v_mfma_f32_16x16x32_bf16 v[46:49], v[156:159], v[192:195], v[46:49]
	v_mfma_f32_16x16x32_bf16 v[30:33], v[156:159], v[200:203], v[30:33]
	v_mfma_f32_16x16x32_bf16 v[26:29], v[160:163], v[200:203], v[26:29]
	v_mfma_f32_16x16x32_bf16 v[10:13], v[160:163], v[208:211], v[10:13]
	v_mfma_f32_16x16x32_bf16 v[14:17], v[156:159], v[208:211], v[14:17]
	v_mfma_f32_16x16x32_bf16 v[54:57], v[164:167], v[180:183], v[54:57]
	v_mfma_f32_16x16x32_bf16 v[50:53], v[168:171], v[180:183], v[50:53]
	v_mfma_f32_16x16x32_bf16 v[34:37], v[168:171], v[188:191], v[34:37]
	v_mfma_f32_16x16x32_bf16 v[38:41], v[164:167], v[188:191], v[38:41]
	v_mfma_f32_16x16x32_bf16 v[22:25], v[164:167], v[196:199], v[22:25]
	v_mfma_f32_16x16x32_bf16 v[18:21], v[168:171], v[196:199], v[18:21]
	v_mfma_f32_16x16x32_bf16 v[2:5], v[168:171], v[204:207], v[2:5]
	v_mfma_f32_16x16x32_bf16 v[6:9], v[164:167], v[204:207], v[6:9]
	v_mfma_f32_16x16x32_bf16 v[54:57], v[172:175], v[184:187], v[54:57]
	v_mfma_f32_16x16x32_bf16 v[50:53], v[176:179], v[184:187], v[50:53]
	v_mfma_f32_16x16x32_bf16 v[34:37], v[176:179], v[192:195], v[34:37]
	v_mfma_f32_16x16x32_bf16 v[38:41], v[172:175], v[192:195], v[38:41]
	v_mfma_f32_16x16x32_bf16 v[22:25], v[172:175], v[200:203], v[22:25]
	v_mfma_f32_16x16x32_bf16 v[18:21], v[176:179], v[200:203], v[18:21]
	v_mfma_f32_16x16x32_bf16 v[2:5], v[176:179], v[208:211], v[2:5]
	v_mfma_f32_16x16x32_bf16 v[6:9], v[172:175], v[208:211], v[6:9]
	s_setprio 0
	s_barrier
	s_add_i32 s20, 0, 0x18000
	v_add_u32_e32 v147, s20, v1
	s_add_i32 s21, 0, 0x1c000
	ds_read_b128 v[148:151], v147
	ds_read_b128 v[152:155], v147 offset:256
	ds_read_b128 v[156:159], v147 offset:8192
	ds_read_b128 v[160:163], v147 offset:8448
	v_add_u32_e32 v147, s21, v1
	ds_read_b128 v[164:167], v147
	ds_read_b128 v[168:171], v147 offset:256
	ds_read_b128 v[172:175], v147 offset:8192
	ds_read_b128 v[176:179], v147 offset:8448
	s_add_u32 s2, s4, 0x104000
	s_addc_u32 s3, s5, 0
	s_mov_b32 m0, s41
	v_lshl_add_u64 v[214:215], s[2:3], 0, v[130:131]
	ds_read_b128 v[180:183], v145 offset:32768
	ds_read_b128 v[184:187], v145 offset:33792
	ds_read_b128 v[188:191], v145 offset:34816
	ds_read_b128 v[192:195], v145 offset:35840
	ds_read_b128 v[196:199], v145 offset:36864
	ds_read_b128 v[200:203], v145 offset:37888
	ds_read_b128 v[204:207], v145 offset:38912
	ds_read_b128 v[208:211], v145 offset:39936
	global_load_lds_dwordx4 v[214:215], off
	v_lshl_add_u64 v[214:215], s[2:3], 0, v[134:135]
	s_mov_b32 m0, s76
	s_nop 0
	global_load_lds_dwordx4 v[214:215], off
	s_waitcnt vmcnt(8)
	s_waitcnt lgkmcnt(0)
	s_barrier
	s_setprio 1
	s_waitcnt lgkmcnt(0)
	v_mfma_f32_16x16x32_bf16 v[126:129], v[148:151], v[180:183], v[126:129]
	v_mfma_f32_16x16x32_bf16 v[122:125], v[152:155], v[180:183], v[122:125]
	v_mfma_f32_16x16x32_bf16 v[106:109], v[152:155], v[188:191], v[106:109]
	v_mfma_f32_16x16x32_bf16 v[110:113], v[148:151], v[188:191], v[110:113]
	v_mfma_f32_16x16x32_bf16 v[94:97], v[148:151], v[196:199], v[94:97]
	v_mfma_f32_16x16x32_bf16 v[90:93], v[152:155], v[196:199], v[90:93]
	v_mfma_f32_16x16x32_bf16 v[74:77], v[152:155], v[204:207], v[74:77]
	v_mfma_f32_16x16x32_bf16 v[78:81], v[148:151], v[204:207], v[78:81]
	v_mfma_f32_16x16x32_bf16 v[126:129], v[156:159], v[184:187], v[126:129]
	v_mfma_f32_16x16x32_bf16 v[122:125], v[160:163], v[184:187], v[122:125]
	v_mfma_f32_16x16x32_bf16 v[106:109], v[160:163], v[192:195], v[106:109]
	v_mfma_f32_16x16x32_bf16 v[110:113], v[156:159], v[192:195], v[110:113]
	v_mfma_f32_16x16x32_bf16 v[94:97], v[156:159], v[200:203], v[94:97]
	v_mfma_f32_16x16x32_bf16 v[90:93], v[160:163], v[200:203], v[90:93]
	v_mfma_f32_16x16x32_bf16 v[74:77], v[160:163], v[208:211], v[74:77]
	v_mfma_f32_16x16x32_bf16 v[78:81], v[156:159], v[208:211], v[78:81]
	v_mfma_f32_16x16x32_bf16 v[118:121], v[164:167], v[180:183], v[118:121]
	v_mfma_f32_16x16x32_bf16 v[114:117], v[168:171], v[180:183], v[114:117]
	v_mfma_f32_16x16x32_bf16 v[98:101], v[168:171], v[188:191], v[98:101]
	v_mfma_f32_16x16x32_bf16 v[102:105], v[164:167], v[188:191], v[102:105]
	v_mfma_f32_16x16x32_bf16 v[86:89], v[164:167], v[196:199], v[86:89]
	v_mfma_f32_16x16x32_bf16 v[82:85], v[168:171], v[196:199], v[82:85]
	v_mfma_f32_16x16x32_bf16 v[66:69], v[168:171], v[204:207], v[66:69]
	v_mfma_f32_16x16x32_bf16 v[70:73], v[164:167], v[204:207], v[70:73]
	v_mfma_f32_16x16x32_bf16 v[118:121], v[172:175], v[184:187], v[118:121]
	v_mfma_f32_16x16x32_bf16 v[114:117], v[176:179], v[184:187], v[114:117]
	v_mfma_f32_16x16x32_bf16 v[98:101], v[176:179], v[192:195], v[98:101]
	v_mfma_f32_16x16x32_bf16 v[102:105], v[172:175], v[192:195], v[102:105]
	v_mfma_f32_16x16x32_bf16 v[86:89], v[172:175], v[200:203], v[86:89]
	v_mfma_f32_16x16x32_bf16 v[82:85], v[176:179], v[200:203], v[82:85]
	v_mfma_f32_16x16x32_bf16 v[66:69], v[176:179], v[208:211], v[66:69]
	v_mfma_f32_16x16x32_bf16 v[70:73], v[172:175], v[208:211], v[70:73]
	s_setprio 0
	s_barrier
	s_add_i32 s2, s20, s18
	v_lshl_add_u64 v[214:215], s[62:63], 0, v[132:133]
	s_mov_b32 m0, s2
	ds_read_b128 v[180:183], v145 offset:49152
	ds_read_b128 v[184:187], v145 offset:50176
	ds_read_b128 v[188:191], v145 offset:51200
	ds_read_b128 v[192:195], v145 offset:52224
	ds_read_b128 v[196:199], v145 offset:53248
	ds_read_b128 v[200:203], v145 offset:54272
	ds_read_b128 v[204:207], v145 offset:55296
	ds_read_b128 v[208:211], v145 offset:56320
	global_load_lds_dwordx4 v[214:215], off
	s_add_i32 m0, s2, 0x2000
	s_add_u32 s2, s60, 0x209000
	v_lshl_add_u64 v[214:215], s[62:63], 0, v[136:137]
	s_addc_u32 s3, s61, 0
	s_add_i32 s4, s21, s18
	global_load_lds_dwordx4 v[214:215], off
	v_lshl_add_u64 v[214:215], s[2:3], 0, v[132:133]
	s_mov_b32 m0, s4
	v_lshl_add_u64 v[140:141], v[140:141], 0, s[14:15]
	global_load_lds_dwordx4 v[214:215], off
	v_lshl_add_u64 v[214:215], s[2:3], 0, v[136:137]
	s_add_i32 m0, s4, 0x2000
	s_nop 0
	global_load_lds_dwordx4 v[214:215], off
	s_mov_b32 m0, s77
	s_nop 0
	global_load_lds_dwordx4 v[140:141], off
	v_lshl_add_u64 v[140:141], v[212:213], 0, s[14:15]
	s_mov_b32 m0, s78
	s_nop 0
	global_load_lds_dwordx4 v[140:141], off
	s_waitcnt vmcnt(8)
	s_waitcnt lgkmcnt(0)
	s_barrier
	s_setprio 1
	s_waitcnt lgkmcnt(0)
	v_mfma_f32_16x16x32_bf16 v[62:65], v[148:151], v[180:183], v[62:65]
	v_mfma_f32_16x16x32_bf16 v[58:61], v[152:155], v[180:183], v[58:61]
	v_mfma_f32_16x16x32_bf16 v[42:45], v[152:155], v[188:191], v[42:45]
	v_mfma_f32_16x16x32_bf16 v[46:49], v[148:151], v[188:191], v[46:49]
	v_mfma_f32_16x16x32_bf16 v[30:33], v[148:151], v[196:199], v[30:33]
	v_mfma_f32_16x16x32_bf16 v[26:29], v[152:155], v[196:199], v[26:29]
	v_mfma_f32_16x16x32_bf16 v[10:13], v[152:155], v[204:207], v[10:13]
	v_mfma_f32_16x16x32_bf16 v[14:17], v[148:151], v[204:207], v[14:17]
	v_mfma_f32_16x16x32_bf16 v[62:65], v[156:159], v[184:187], v[62:65]
	v_mfma_f32_16x16x32_bf16 v[58:61], v[160:163], v[184:187], v[58:61]
	v_mfma_f32_16x16x32_bf16 v[42:45], v[160:163], v[192:195], v[42:45]
	v_mfma_f32_16x16x32_bf16 v[46:49], v[156:159], v[192:195], v[46:49]
	v_mfma_f32_16x16x32_bf16 v[30:33], v[156:159], v[200:203], v[30:33]
	v_mfma_f32_16x16x32_bf16 v[26:29], v[160:163], v[200:203], v[26:29]
	v_mfma_f32_16x16x32_bf16 v[10:13], v[160:163], v[208:211], v[10:13]
	v_mfma_f32_16x16x32_bf16 v[14:17], v[156:159], v[208:211], v[14:17]
	v_mfma_f32_16x16x32_bf16 v[54:57], v[164:167], v[180:183], v[54:57]
	v_mfma_f32_16x16x32_bf16 v[50:53], v[168:171], v[180:183], v[50:53]
	v_mfma_f32_16x16x32_bf16 v[34:37], v[168:171], v[188:191], v[34:37]
	v_mfma_f32_16x16x32_bf16 v[38:41], v[164:167], v[188:191], v[38:41]
	v_mfma_f32_16x16x32_bf16 v[22:25], v[164:167], v[196:199], v[22:25]
	v_mfma_f32_16x16x32_bf16 v[18:21], v[168:171], v[196:199], v[18:21]
	v_mfma_f32_16x16x32_bf16 v[2:5], v[168:171], v[204:207], v[2:5]
	v_mfma_f32_16x16x32_bf16 v[6:9], v[164:167], v[204:207], v[6:9]
	v_mfma_f32_16x16x32_bf16 v[54:57], v[172:175], v[184:187], v[54:57]
	v_mfma_f32_16x16x32_bf16 v[50:53], v[176:179], v[184:187], v[50:53]
	v_mfma_f32_16x16x32_bf16 v[34:37], v[176:179], v[192:195], v[34:37]
	v_mfma_f32_16x16x32_bf16 v[38:41], v[172:175], v[192:195], v[38:41]
	v_mfma_f32_16x16x32_bf16 v[22:25], v[172:175], v[200:203], v[22:25]
	v_mfma_f32_16x16x32_bf16 v[18:21], v[176:179], v[200:203], v[18:21]
	v_mfma_f32_16x16x32_bf16 v[2:5], v[176:179], v[208:211], v[2:5]
	v_mfma_f32_16x16x32_bf16 v[6:9], v[172:175], v[208:211], v[6:9]
	s_setprio 0
	s_barrier
	s_add_i32 s2, s90, 2
	s_cmp_gt_u32 s90, 61
	s_cbranch_scc1 .LBB0_802
	s_mov_b32 s90, s2
	s_branch .LBB0_767

.LBB0_933:
	s_lshl_b32 s2, s88, 7
	s_add_u32 s26, s34, s2
	s_addc_u32 s27, s35, 0
	s_add_u32 s46, s26, 0x100
	s_addc_u32 s47, s27, 0
	s_and_b64 s[2:3], s[44:45], exec
	v_add_u32_e32 v187, s36, v182
	s_mul_i32 s2, s88, 0x88800
	ds_read_b128 v[128:131], v187
	ds_read_b128 v[132:135], v187 offset:256
	ds_read_b128 v[178:181], v187 offset:8192
	ds_read_b128 v[188:191], v187 offset:8448
	v_add_u32_e32 v187, s37, v182
	s_cselect_b32 s51, s47, s23
	s_cselect_b32 s50, s46, s22
	s_add_u32 s2, s40, s2
	ds_read_b128 v[192:195], v187
	ds_read_b128 v[196:199], v187 offset:256
	ds_read_b128 v[200:203], v187 offset:8192
	ds_read_b128 v[204:207], v187 offset:8448
	s_addc_u32 s3, s41, 0
	s_add_u32 s46, s2, 0x111000
	s_addc_u32 s47, s3, 0
	s_and_b64 s[2:3], s[44:45], exec
	s_cselect_b32 s44, s46, s87
	s_cselect_b32 s45, s47, s21
	s_add_u32 s46, s44, 0x88800
	s_addc_u32 s47, s45, 0
	s_add_u32 s2, s26, 0x404080
	s_addc_u32 s3, s27, 0
	v_lshl_add_u64 v[240:241], s[2:3], 0, v[136:137]
	s_add_i32 m0, s33, 0xc000
	ds_read_b128 v[208:211], v185
	ds_read_b128 v[212:215], v185 offset:1024
	ds_read_b128 v[216:219], v185 offset:2048
	ds_read_b128 v[220:223], v185 offset:3072
	ds_read_b128 v[224:227], v185 offset:4096
	ds_read_b128 v[228:231], v185 offset:5120
	ds_read_b128 v[232:235], v185 offset:6144
	ds_read_b128 v[236:239], v185 offset:7168
	global_load_lds_dwordx4 v[240:241], off
	v_lshl_add_u64 v[240:241], s[2:3], 0, v[140:141]
	s_add_i32 m0, s33, 0xe000
	s_nop 0
	global_load_lds_dwordx4 v[240:241], off
	s_waitcnt vmcnt(8)
	s_waitcnt lgkmcnt(0)
	s_barrier
	s_setprio 1
	s_waitcnt lgkmcnt(0)
	v_mfma_f32_16x16x32_bf16 v[124:127], v[128:131], v[208:211], v[124:127]
	v_mfma_f32_16x16x32_bf16 v[120:123], v[132:135], v[208:211], v[120:123]
	v_mfma_f32_16x16x32_bf16 v[104:107], v[132:135], v[216:219], v[104:107]
	v_mfma_f32_16x16x32_bf16 v[108:111], v[128:131], v[216:219], v[108:111]
	v_mfma_f32_16x16x32_bf16 v[92:95], v[128:131], v[224:227], v[92:95]
	v_mfma_f32_16x16x32_bf16 v[88:91], v[132:135], v[224:227], v[88:91]
	v_mfma_f32_16x16x32_bf16 v[72:75], v[132:135], v[232:235], v[72:75]
	v_mfma_f32_16x16x32_bf16 v[76:79], v[128:131], v[232:235], v[76:79]
	v_mfma_f32_16x16x32_bf16 v[124:127], v[178:181], v[212:215], v[124:127]
	v_mfma_f32_16x16x32_bf16 v[120:123], v[188:191], v[212:215], v[120:123]
	v_mfma_f32_16x16x32_bf16 v[104:107], v[188:191], v[220:223], v[104:107]
	v_mfma_f32_16x16x32_bf16 v[108:111], v[178:181], v[220:223], v[108:111]
	v_mfma_f32_16x16x32_bf16 v[92:95], v[178:181], v[228:231], v[92:95]
	v_mfma_f32_16x16x32_bf16 v[88:91], v[188:191], v[228:231], v[88:91]
	v_mfma_f32_16x16x32_bf16 v[72:75], v[188:191], v[236:239], v[72:75]
	v_mfma_f32_16x16x32_bf16 v[76:79], v[178:181], v[236:239], v[76:79]
	v_mfma_f32_16x16x32_bf16 v[116:119], v[192:195], v[208:211], v[116:119]
	v_mfma_f32_16x16x32_bf16 v[112:115], v[196:199], v[208:211], v[112:115]
	v_mfma_f32_16x16x32_bf16 v[96:99], v[196:199], v[216:219], v[96:99]
	v_mfma_f32_16x16x32_bf16 v[100:103], v[192:195], v[216:219], v[100:103]
	v_mfma_f32_16x16x32_bf16 v[84:87], v[192:195], v[224:227], v[84:87]
	v_mfma_f32_16x16x32_bf16 v[80:83], v[196:199], v[224:227], v[80:83]
	v_mfma_f32_16x16x32_bf16 v[64:67], v[196:199], v[232:235], v[64:67]
	v_mfma_f32_16x16x32_bf16 v[68:71], v[192:195], v[232:235], v[68:71]
	v_mfma_f32_16x16x32_bf16 v[116:119], v[200:203], v[212:215], v[116:119]
	v_mfma_f32_16x16x32_bf16 v[112:115], v[204:207], v[212:215], v[112:115]
	v_mfma_f32_16x16x32_bf16 v[96:99], v[204:207], v[220:223], v[96:99]
	v_mfma_f32_16x16x32_bf16 v[100:103], v[200:203], v[220:223], v[100:103]
	v_mfma_f32_16x16x32_bf16 v[84:87], v[200:203], v[228:231], v[84:87]
	v_mfma_f32_16x16x32_bf16 v[80:83], v[204:207], v[228:231], v[80:83]
	v_mfma_f32_16x16x32_bf16 v[64:67], v[204:207], v[236:239], v[64:67]
	v_mfma_f32_16x16x32_bf16 v[68:71], v[200:203], v[236:239], v[68:71]
	s_setprio 0
	s_barrier
	s_add_i32 s2, s36, s31
	v_lshl_add_u64 v[240:241], s[44:45], 0, v[138:139]
	s_mov_b32 m0, s2
	ds_read_b128 v[208:211], v185 offset:16384
	ds_read_b128 v[212:215], v185 offset:17408
	ds_read_b128 v[216:219], v185 offset:18432
	ds_read_b128 v[220:223], v185 offset:19456
	ds_read_b128 v[224:227], v185 offset:20480
	ds_read_b128 v[228:231], v185 offset:21504
	ds_read_b128 v[232:235], v185 offset:22528
	ds_read_b128 v[236:239], v185 offset:23552
	global_load_lds_dwordx4 v[240:241], off
	v_lshl_add_u64 v[242:243], s[44:45], 0, v[142:143]
	s_add_i32 m0, s2, 0x2000
	s_add_i32 s2, s37, s31
	global_load_lds_dwordx4 v[242:243], off
	v_lshl_add_u64 v[240:241], v[240:241], 0, s[4:5]
	s_mov_b32 m0, s2
	s_nop 0
	global_load_lds_dwordx4 v[240:241], off
	v_lshl_add_u64 v[240:241], v[242:243], 0, s[4:5]
	s_add_i32 m0, s2, 0x2000
	v_lshl_add_u64 v[242:243], s[50:51], 0, v[140:141]
	global_load_lds_dwordx4 v[240:241], off
	v_lshl_add_u64 v[240:241], s[50:51], 0, v[136:137]
	s_mov_b32 m0, s33
	s_nop 0
	global_load_lds_dwordx4 v[240:241], off
	s_mov_b32 m0, s72
	s_nop 0
	global_load_lds_dwordx4 v[242:243], off
	s_waitcnt vmcnt(8)
	s_waitcnt lgkmcnt(0)
	s_barrier
	s_setprio 1
	s_waitcnt lgkmcnt(0)
	v_mfma_f32_16x16x32_bf16 v[60:63], v[128:131], v[208:211], v[60:63]
	v_mfma_f32_16x16x32_bf16 v[56:59], v[132:135], v[208:211], v[56:59]
	v_mfma_f32_16x16x32_bf16 v[40:43], v[132:135], v[216:219], v[40:43]
	v_mfma_f32_16x16x32_bf16 v[44:47], v[128:131], v[216:219], v[44:47]
	v_mfma_f32_16x16x32_bf16 v[28:31], v[128:131], v[224:227], v[28:31]
	v_mfma_f32_16x16x32_bf16 v[24:27], v[132:135], v[224:227], v[24:27]
	v_mfma_f32_16x16x32_bf16 v[8:11], v[132:135], v[232:235], v[8:11]
	v_mfma_f32_16x16x32_bf16 v[12:15], v[128:131], v[232:235], v[12:15]
	v_mfma_f32_16x16x32_bf16 v[60:63], v[178:181], v[212:215], v[60:63]
	v_mfma_f32_16x16x32_bf16 v[56:59], v[188:191], v[212:215], v[56:59]
	v_mfma_f32_16x16x32_bf16 v[40:43], v[188:191], v[220:223], v[40:43]
	v_mfma_f32_16x16x32_bf16 v[44:47], v[178:181], v[220:223], v[44:47]
	v_mfma_f32_16x16x32_bf16 v[28:31], v[178:181], v[228:231], v[28:31]
	v_mfma_f32_16x16x32_bf16 v[24:27], v[188:191], v[228:231], v[24:27]
	v_mfma_f32_16x16x32_bf16 v[8:11], v[188:191], v[236:239], v[8:11]
	v_mfma_f32_16x16x32_bf16 v[12:15], v[178:181], v[236:239], v[12:15]
	v_mfma_f32_16x16x32_bf16 v[52:55], v[192:195], v[208:211], v[52:55]
	v_mfma_f32_16x16x32_bf16 v[48:51], v[196:199], v[208:211], v[48:51]
	v_mfma_f32_16x16x32_bf16 v[32:35], v[196:199], v[216:219], v[32:35]
	v_mfma_f32_16x16x32_bf16 v[36:39], v[192:195], v[216:219], v[36:39]
	v_mfma_f32_16x16x32_bf16 v[20:23], v[192:195], v[224:227], v[20:23]
	v_mfma_f32_16x16x32_bf16 v[16:19], v[196:199], v[224:227], v[16:19]
	v_mfma_f32_16x16x32_bf16 v[0:3], v[196:199], v[232:235], v[0:3]
	v_mfma_f32_16x16x32_bf16 v[4:7], v[192:195], v[232:235], v[4:7]
	v_mfma_f32_16x16x32_bf16 v[52:55], v[200:203], v[212:215], v[52:55]
	v_mfma_f32_16x16x32_bf16 v[48:51], v[204:207], v[212:215], v[48:51]
	v_mfma_f32_16x16x32_bf16 v[32:35], v[204:207], v[220:223], v[32:35]
	v_mfma_f32_16x16x32_bf16 v[36:39], v[200:203], v[220:223], v[36:39]
	v_mfma_f32_16x16x32_bf16 v[20:23], v[200:203], v[228:231], v[20:23]
	v_mfma_f32_16x16x32_bf16 v[16:19], v[204:207], v[228:231], v[16:19]
	v_mfma_f32_16x16x32_bf16 v[0:3], v[204:207], v[236:239], v[0:3]
	v_mfma_f32_16x16x32_bf16 v[4:7], v[200:203], v[236:239], v[4:7]
	s_setprio 0
	s_barrier
	s_add_i32 s26, 0, 0x18000
	v_add_u32_e32 v187, s26, v182
	s_add_i32 s27, 0, 0x1c000
	ds_read_b128 v[128:131], v187
	ds_read_b128 v[132:135], v187 offset:256
	ds_read_b128 v[178:181], v187 offset:8192
	ds_read_b128 v[188:191], v187 offset:8448
	v_add_u32_e32 v187, s27, v182
	ds_read_b128 v[192:195], v187
	ds_read_b128 v[196:199], v187 offset:256
	ds_read_b128 v[200:203], v187 offset:8192
	ds_read_b128 v[204:207], v187 offset:8448
	s_add_u32 s2, s50, 0x404000
	s_addc_u32 s3, s51, 0
	s_mov_b32 m0, s73
	v_lshl_add_u64 v[244:245], s[2:3], 0, v[136:137]
	ds_read_b128 v[208:211], v185 offset:32768
	ds_read_b128 v[212:215], v185 offset:33792
	ds_read_b128 v[216:219], v185 offset:34816
	ds_read_b128 v[220:223], v185 offset:35840
	ds_read_b128 v[224:227], v185 offset:36864
	ds_read_b128 v[228:231], v185 offset:37888
	ds_read_b128 v[232:235], v185 offset:38912
	ds_read_b128 v[236:239], v185 offset:39936
	global_load_lds_dwordx4 v[244:245], off
	v_lshl_add_u64 v[244:245], s[2:3], 0, v[140:141]
	s_mov_b32 m0, s74
	s_nop 0
	global_load_lds_dwordx4 v[244:245], off
	s_waitcnt vmcnt(8)
	s_waitcnt lgkmcnt(0)
	s_barrier
	s_setprio 1
	s_waitcnt lgkmcnt(0)
	v_mfma_f32_16x16x32_bf16 v[124:127], v[128:131], v[208:211], v[124:127]
	v_mfma_f32_16x16x32_bf16 v[120:123], v[132:135], v[208:211], v[120:123]
	v_mfma_f32_16x16x32_bf16 v[104:107], v[132:135], v[216:219], v[104:107]
	v_mfma_f32_16x16x32_bf16 v[108:111], v[128:131], v[216:219], v[108:111]
	v_mfma_f32_16x16x32_bf16 v[92:95], v[128:131], v[224:227], v[92:95]
	v_mfma_f32_16x16x32_bf16 v[88:91], v[132:135], v[224:227], v[88:91]
	v_mfma_f32_16x16x32_bf16 v[72:75], v[132:135], v[232:235], v[72:75]
	v_mfma_f32_16x16x32_bf16 v[76:79], v[128:131], v[232:235], v[76:79]
	v_mfma_f32_16x16x32_bf16 v[124:127], v[178:181], v[212:215], v[124:127]
	v_mfma_f32_16x16x32_bf16 v[120:123], v[188:191], v[212:215], v[120:123]
	v_mfma_f32_16x16x32_bf16 v[104:107], v[188:191], v[220:223], v[104:107]
	v_mfma_f32_16x16x32_bf16 v[108:111], v[178:181], v[220:223], v[108:111]
	v_mfma_f32_16x16x32_bf16 v[92:95], v[178:181], v[228:231], v[92:95]
	v_mfma_f32_16x16x32_bf16 v[88:91], v[188:191], v[228:231], v[88:91]
	v_mfma_f32_16x16x32_bf16 v[72:75], v[188:191], v[236:239], v[72:75]
	v_mfma_f32_16x16x32_bf16 v[76:79], v[178:181], v[236:239], v[76:79]
	v_mfma_f32_16x16x32_bf16 v[116:119], v[192:195], v[208:211], v[116:119]
	v_mfma_f32_16x16x32_bf16 v[112:115], v[196:199], v[208:211], v[112:115]
	v_mfma_f32_16x16x32_bf16 v[96:99], v[196:199], v[216:219], v[96:99]
	v_mfma_f32_16x16x32_bf16 v[100:103], v[192:195], v[216:219], v[100:103]
	v_mfma_f32_16x16x32_bf16 v[84:87], v[192:195], v[224:227], v[84:87]
	v_mfma_f32_16x16x32_bf16 v[80:83], v[196:199], v[224:227], v[80:83]
	v_mfma_f32_16x16x32_bf16 v[64:67], v[196:199], v[232:235], v[64:67]
	v_mfma_f32_16x16x32_bf16 v[68:71], v[192:195], v[232:235], v[68:71]
	v_mfma_f32_16x16x32_bf16 v[116:119], v[200:203], v[212:215], v[116:119]
	v_mfma_f32_16x16x32_bf16 v[112:115], v[204:207], v[212:215], v[112:115]
	v_mfma_f32_16x16x32_bf16 v[96:99], v[204:207], v[220:223], v[96:99]
	v_mfma_f32_16x16x32_bf16 v[100:103], v[200:203], v[220:223], v[100:103]
	v_mfma_f32_16x16x32_bf16 v[84:87], v[200:203], v[228:231], v[84:87]
	v_mfma_f32_16x16x32_bf16 v[80:83], v[204:207], v[228:231], v[80:83]
	v_mfma_f32_16x16x32_bf16 v[64:67], v[204:207], v[236:239], v[64:67]
	v_mfma_f32_16x16x32_bf16 v[68:71], v[200:203], v[236:239], v[68:71]
	s_setprio 0
	s_barrier
	s_add_i32 s2, s26, s31
	v_lshl_add_u64 v[244:245], s[46:47], 0, v[138:139]
	s_mov_b32 m0, s2
	ds_read_b128 v[208:211], v185 offset:49152
	ds_read_b128 v[212:215], v185 offset:50176
	ds_read_b128 v[216:219], v185 offset:51200
	ds_read_b128 v[220:223], v185 offset:52224
	ds_read_b128 v[224:227], v185 offset:53248
	ds_read_b128 v[228:231], v185 offset:54272
	ds_read_b128 v[232:235], v185 offset:55296
	ds_read_b128 v[236:239], v185 offset:56320
	global_load_lds_dwordx4 v[244:245], off
	s_add_i32 m0, s2, 0x2000
	s_add_u32 s2, s44, 0x89000
	v_lshl_add_u64 v[244:245], s[46:47], 0, v[142:143]
	s_addc_u32 s3, s45, 0
	s_add_i32 s26, s27, s31
	global_load_lds_dwordx4 v[244:245], off
	v_lshl_add_u64 v[244:245], s[2:3], 0, v[138:139]
	s_mov_b32 m0, s26
	v_lshl_add_u64 v[240:241], v[240:241], 0, s[12:13]
	global_load_lds_dwordx4 v[244:245], off
	v_lshl_add_u64 v[244:245], s[2:3], 0, v[142:143]
	s_add_i32 m0, s26, 0x2000
	s_nop 0
	global_load_lds_dwordx4 v[244:245], off
	s_mov_b32 m0, s78
	s_nop 0
	global_load_lds_dwordx4 v[240:241], off
	v_lshl_add_u64 v[240:241], v[242:243], 0, s[12:13]
	s_mov_b32 m0, s79
	s_nop 0
	global_load_lds_dwordx4 v[240:241], off
	s_waitcnt vmcnt(8)
	s_waitcnt lgkmcnt(0)
	s_barrier
	s_setprio 1
	s_waitcnt lgkmcnt(0)
	v_mfma_f32_16x16x32_bf16 v[60:63], v[128:131], v[208:211], v[60:63]
	v_mfma_f32_16x16x32_bf16 v[56:59], v[132:135], v[208:211], v[56:59]
	v_mfma_f32_16x16x32_bf16 v[40:43], v[132:135], v[216:219], v[40:43]
	v_mfma_f32_16x16x32_bf16 v[44:47], v[128:131], v[216:219], v[44:47]
	v_mfma_f32_16x16x32_bf16 v[28:31], v[128:131], v[224:227], v[28:31]
	v_mfma_f32_16x16x32_bf16 v[24:27], v[132:135], v[224:227], v[24:27]
	v_mfma_f32_16x16x32_bf16 v[8:11], v[132:135], v[232:235], v[8:11]
	v_mfma_f32_16x16x32_bf16 v[12:15], v[128:131], v[232:235], v[12:15]
	v_mfma_f32_16x16x32_bf16 v[60:63], v[178:181], v[212:215], v[60:63]
	v_mfma_f32_16x16x32_bf16 v[56:59], v[188:191], v[212:215], v[56:59]
	v_mfma_f32_16x16x32_bf16 v[40:43], v[188:191], v[220:223], v[40:43]
	v_mfma_f32_16x16x32_bf16 v[44:47], v[178:181], v[220:223], v[44:47]
	v_mfma_f32_16x16x32_bf16 v[28:31], v[178:181], v[228:231], v[28:31]
	v_mfma_f32_16x16x32_bf16 v[24:27], v[188:191], v[228:231], v[24:27]
	v_mfma_f32_16x16x32_bf16 v[8:11], v[188:191], v[236:239], v[8:11]
	v_mfma_f32_16x16x32_bf16 v[12:15], v[178:181], v[236:239], v[12:15]
	v_mfma_f32_16x16x32_bf16 v[52:55], v[192:195], v[208:211], v[52:55]
	v_mfma_f32_16x16x32_bf16 v[48:51], v[196:199], v[208:211], v[48:51]
	v_mfma_f32_16x16x32_bf16 v[32:35], v[196:199], v[216:219], v[32:35]
	v_mfma_f32_16x16x32_bf16 v[36:39], v[192:195], v[216:219], v[36:39]
	v_mfma_f32_16x16x32_bf16 v[20:23], v[192:195], v[224:227], v[20:23]
	v_mfma_f32_16x16x32_bf16 v[16:19], v[196:199], v[224:227], v[16:19]
	v_mfma_f32_16x16x32_bf16 v[0:3], v[196:199], v[232:235], v[0:3]
	v_mfma_f32_16x16x32_bf16 v[4:7], v[192:195], v[232:235], v[4:7]
	v_mfma_f32_16x16x32_bf16 v[52:55], v[200:203], v[212:215], v[52:55]
	v_mfma_f32_16x16x32_bf16 v[48:51], v[204:207], v[212:215], v[48:51]
	v_mfma_f32_16x16x32_bf16 v[32:35], v[204:207], v[220:223], v[32:35]
	v_mfma_f32_16x16x32_bf16 v[36:39], v[200:203], v[220:223], v[36:39]
	v_mfma_f32_16x16x32_bf16 v[20:23], v[200:203], v[228:231], v[20:23]
	v_mfma_f32_16x16x32_bf16 v[16:19], v[204:207], v[228:231], v[16:19]
	v_mfma_f32_16x16x32_bf16 v[0:3], v[204:207], v[236:239], v[0:3]
	v_mfma_f32_16x16x32_bf16 v[4:7], v[200:203], v[236:239], v[4:7]
	s_setprio 0
	s_barrier
	s_add_i32 s2, s88, 2
	s_cmpk_gt_u32 s88, 0xfd
	s_cbranch_scc1 .LBB0_939
	s_mov_b32 s88, s2
	s_branch .LBB0_904
